# G1: the eight value-row loads of a task issued behind the key-row loads at the task top (were two groups waited on right after issue); on top of v46
# speedup vs baseline: 1.0076x; 1.0040x over previous
; __device__ __forceinline__ bf16_t f2bf(float f) { return (bf16_t)f2bf_u(f); }
; __device__ __forceinline__ float bf_lo(unsigned u) { return __uint_as_float(u << 16); }
; __device__ __forceinline__ float bf_hi(unsigned u) { return __uint_as_float(u & 0xffff0000u); }
; __device__ void phaseG1_task(const Params& p, int task, char* lds) {
;     ...
;     if (tid < 128) ((float*)(p.ws + OFF_DEC))[task * 128 + tid] = __expf(bc[63 * 128 + tid]);
;     {
;         f32x4* bg = (f32x4*)(p.ws + OFF_M) + (size_t)task * 2048;
; #pragma unroll
;         for (int i = 0; i < 8; i++) bg[i * 256 + tid] = ((const f32x4*)bc)[i * 256 + tid];
;     }
;     {
;         const int s = lane, dc = wave * 32;
;         const bf16_t* kp = Z + (size_t)(tok0 + s) * ZC + ZK_G + h * 128 + dc;
; #pragma unroll
;         for (int v4 = 0; v4 < 4; v4++) {
;             const u32x4 kv = *(const u32x4*)(kp + v4 * 8);
;             const unsigned kw[4] = {kv.x, kv.y, kv.z, kv.w};
; #pragma unroll
;             for (int j = 0; j < 8; j++) {
;                 const int d = dc + v4 * 8 + j;
;                 const float kval = (j & 1) ? bf_hi(kw[j >> 1]) : bf_lo(kw[j >> 1]);
;                 klT[d * 72 + s] = f2bf(kval * __expf(bc[63 * 128 + d] - bc[s * 128 + d]));
;             }
;         }
.LBB0_378:
	s_or_b64 exec, exec, s[8:9]
	s_lshl_b32 s8, s14, 4
	s_lshl_b32 s9, s14, 6
	v_lshlrev_b32_e32 v8, 4, v0
	s_and_b32 s8, s8, 0xfffff800
	s_and_b32 s9, s9, 0x7c0
	s_ashr_i32 s15, s14, 31
	v_add_u32_e32 v10, s33, v8
	s_or_b32 s10, s8, s9
	s_lshl_b64 s[8:9], s[14:15], 15
	ds_read_b128 v[0:3], v10
	ds_read_b128 v[4:7], v10 offset:4096
	s_add_u32 s8, s6, s8
	s_addc_u32 s9, s7, s9
	s_add_u32 s8, s8, 0x3c00000
	s_addc_u32 s9, s9, 0
	s_waitcnt lgkmcnt(1)
	global_store_dwordx4 v8, v[0:3], s[8:9]
	ds_read_b128 v[0:3], v10 offset:8192
	v_or_b32_e32 v11, 0x1000, v8
	s_waitcnt lgkmcnt(1)
	global_store_dwordx4 v11, v[4:7], s[8:9]
	ds_read_b128 v[4:7], v10 offset:12288
	v_or_b32_e32 v11, 0x2000, v8
	s_waitcnt lgkmcnt(1)
	global_store_dwordx4 v11, v[0:3], s[8:9]
	ds_read_b128 v[0:3], v10 offset:16384
	v_or_b32_e32 v11, 0x3000, v8
	s_waitcnt lgkmcnt(1)
	global_store_dwordx4 v11, v[4:7], s[8:9]
	v_or_b32_e32 v11, 0x4000, v8
	ds_read_b128 v[4:7], v10 offset:20480
	s_waitcnt lgkmcnt(1)
	global_store_dwordx4 v11, v[0:3], s[8:9]
	ds_read_b128 v[0:3], v10 offset:24576
	ds_read_b128 v[14:17], v10 offset:28672
	v_or_b32_e32 v11, 0x5000, v8
	s_waitcnt lgkmcnt(2)
	global_store_dwordx4 v11, v[4:7], s[8:9]
	v_and_b32_e32 v18, 63, v12
	v_lshrrev_b32_e32 v13, 1, v12
	v_or_b32_e32 v4, 0x6000, v8
	s_waitcnt lgkmcnt(1)
	global_store_dwordx4 v4, v[0:3], s[8:9]
	s_lshl_b32 s18, s18, 1
	s_nop 0
	v_or_b32_e32 v0, 0x7000, v8
	s_waitcnt lgkmcnt(0)
	global_store_dwordx4 v0, v[14:17], s[8:9]
	v_or_b32_e32 v2, s10, v18
	v_mov_b64_e32 v[0:1], s[6:7]
	v_mad_i64_i32 v[0:1], s[6:7], v2, s38, v[0:1]
	v_and_b32_e32 v14, 0x60, v13
	v_lshl_add_u64 v[10:11], v[0:1], 0, s[20:21]
	v_lshl_add_u64 v[0:1], v[10:11], 0, s[18:19]
	v_lshlrev_b32_e32 v8, 1, v14
	v_lshl_add_u64 v[4:5], v[0:1], 0, v[8:9]
	global_load_dwordx4 v[22:25], v[4:5], off offset:1024
	global_load_dwordx4 v[26:29], v[4:5], off offset:1040
	v_lshl_add_u32 v16, v14, 2, s33
	v_lshl_add_u32 v17, v18, 9, v16
	ds_read_b128 v[30:33], v16 offset:32256
	ds_read_b128 v[34:37], v16 offset:32272
	ds_read_b128 v[38:41], v17
	v_mul_u32_u24_e32 v0, 0x48, v14
	ds_read_b128 v[42:45], v17 offset:16
	v_or_b32_e32 v1, 1, v14
	v_or_b32_e32 v0, v0, v18
	s_waitcnt lgkmcnt(1)
	v_sub_f32_e32 v30, v30, v38
	v_sub_f32_e32 v31, v31, v39
	v_sub_f32_e32 v32, v32, v40
	v_sub_f32_e32 v33, v33, v41
	v_mul_f32_e32 v30, 0x3fb8aa3b, v30
	v_mul_f32_e32 v31, 0x3fb8aa3b, v31
	v_mul_f32_e32 v32, 0x3fb8aa3b, v32
	v_mul_f32_e32 v33, 0x3fb8aa3b, v33
	v_exp_f32_e32 v30, v30
	v_exp_f32_e32 v31, v31
	v_exp_f32_e32 v32, v32
	v_exp_f32_e32 v33, v33
	v_lshlrev_b32_e32 v15, 1, v18
	v_mul_u32_u24_e32 v1, 0x90, v1
	v_lshl_add_u32 v21, v0, 1, s33
	v_add3_u32 v19, s33, v1, v15
	global_load_dwordx4 v[0:3], v[4:5], off offset:1072
	s_nop 0
	global_load_dwordx4 v[4:7], v[4:5], off offset:1056
	s_lshl_b32 s18, s47, 9
	v_lshl_add_u64 v[130:131], v[10:11], 0, s[18:19]
	v_lshl_add_u64 v[130:131], v[130:131], 0, v[8:9]
	global_load_dwordx4 v[132:135], v[130:131], off offset:2048
	global_load_dwordx4 v[136:139], v[130:131], off offset:2064
	global_load_dwordx4 v[140:143], v[130:131], off offset:2080
	global_load_dwordx4 v[144:147], v[130:131], off offset:2096
	global_load_dwordx4 v[148:151], v[130:131], off offset:2304
	global_load_dwordx4 v[152:155], v[130:131], off offset:2320
	global_load_dwordx4 v[160:163], v[130:131], off offset:2336
	global_load_dwordx4 v[164:167], v[130:131], off offset:2352
	s_lshl_b64 s[6:7], s[14:15], 16
	s_add_u32 s4, s4, s6
	s_addc_u32 s5, s5, s7
	s_add_i32 s14, s14, s0
	s_add_i32 s2, s2, s3
	s_add_i32 s36, s36, s37
	s_cmpk_gt_i32 s14, 0x3ff
	s_waitcnt vmcnt(11)
	v_lshlrev_b32_e32 v38, 16, v22
	v_and_b32_e32 v22, 0xffff0000, v22
	v_lshlrev_b32_e32 v39, 16, v23
	v_and_b32_e32 v23, 0xffff0000, v23
	v_mul_f32_e32 v30, v30, v38
	v_mul_f32_e32 v22, v31, v22
	v_mul_f32_e32 v31, v32, v39
	v_mul_f32_e32 v23, v33, v23
	v_bfe_u32 v32, v30, 16, 1
	v_bfe_u32 v33, v22, 16, 1
	v_bfe_u32 v38, v31, 16, 1
	v_add3_u32 v30, v30, v32, s46
	v_add3_u32 v22, v22, v33, s46
	v_add3_u32 v31, v31, v38, s46
	ds_write_b16_d16_hi v21, v30 offset:36864
	ds_write_b16_d16_hi v19, v22 offset:36864
	ds_write_b16_d16_hi v19, v31 offset:37008
	v_bfe_u32 v22, v23, 16, 1
	v_add3_u32 v22, v23, v22, s46
	ds_write_b16_d16_hi v19, v22 offset:37152
	s_waitcnt lgkmcnt(4)
	v_sub_f32_e32 v22, v34, v42
	v_mul_f32_e32 v22, 0x3fb8aa3b, v22
	v_exp_f32_e32 v22, v22
	v_lshlrev_b32_e32 v23, 16, v24
	v_sub_f32_e32 v34, v35, v43
	v_mul_f32_e32 v34, 0x3fb8aa3b, v34
	v_mul_f32_e32 v22, v22, v23
	v_bfe_u32 v23, v22, 16, 1
	v_exp_f32_e32 v34, v34
	v_add3_u32 v22, v22, v23, s46
	ds_read_b128 v[30:33], v16 offset:32288
	ds_read_b128 v[38:41], v17 offset:32
	ds_write_b16_d16_hi v19, v22 offset:37296
	v_and_b32_e32 v22, 0xffff0000, v24
	v_sub_f32_e32 v24, v36, v44
	v_mul_f32_e32 v24, 0x3fb8aa3b, v24
	v_mul_f32_e32 v22, v34, v22
	v_exp_f32_e32 v24, v24
	v_bfe_u32 v23, v22, 16, 1
	v_add3_u32 v22, v22, v23, s46
	ds_write_b16_d16_hi v19, v22 offset:37440
	v_lshlrev_b32_e32 v22, 16, v25
	v_mul_f32_e32 v22, v24, v22
	v_sub_f32_e32 v24, v37, v45
	v_mul_f32_e32 v24, 0x3fb8aa3b, v24
	v_exp_f32_e32 v24, v24
	v_bfe_u32 v23, v22, 16, 1
	v_add3_u32 v22, v22, v23, s46
	ds_write_b16_d16_hi v19, v22 offset:37584
	v_and_b32_e32 v22, 0xffff0000, v25
	v_mul_f32_e32 v22, v24, v22
	v_bfe_u32 v23, v22, 16, 1
	v_add3_u32 v22, v22, v23, s46
	s_waitcnt lgkmcnt(3)
	v_sub_f32_e32 v23, v30, v38
	v_mul_f32_e32 v23, 0x3fb8aa3b, v23
	v_exp_f32_e32 v23, v23
	s_waitcnt vmcnt(10)
; __device__ __forceinline__ bf16_t f2bf(float f) { return (bf16_t)f2bf_u(f); }
; __device__ __forceinline__ float bf_lo(unsigned u) { return __uint_as_float(u << 16); }
; __device__ __forceinline__ float bf_hi(unsigned u) { return __uint_as_float(u & 0xffff0000u); }
; __device__ void phaseG1_task(const Params& p, int task, char* lds) {
;     ...
;         const int s = lane, dc = wave * 32;
;         const bf16_t* kp = Z + (size_t)(tok0 + s) * ZC + ZK_G + h * 128 + dc;
; #pragma unroll
;         for (int v4 = 0; v4 < 4; v4++) {
;             const u32x4 kv = *(const u32x4*)(kp + v4 * 8);
;             const unsigned kw[4] = {kv.x, kv.y, kv.z, kv.w};
; #pragma unroll
;             for (int j = 0; j < 8; j++) {
;                 const int d = dc + v4 * 8 + j;
;                 const float kval = (j & 1) ? bf_hi(kw[j >> 1]) : bf_lo(kw[j >> 1]);
;                 klT[d * 72 + s] = f2bf(kval * __expf(bc[63 * 128 + d] - bc[s * 128 + d]));
;             }
;         }
	v_lshlrev_b32_e32 v24, 16, v26
	ds_read_b128 v[34:37], v16 offset:32304
	ds_read_b128 v[42:45], v17 offset:48
	ds_write_b16_d16_hi v19, v22 offset:37728
	v_mul_f32_e32 v23, v23, v24
	v_bfe_u32 v24, v23, 16, 1
	v_add3_u32 v23, v23, v24, s46
	v_sub_f32_e32 v24, v31, v39
	v_or_b32_e32 v22, 8, v14
	v_mul_f32_e32 v24, 0x3fb8aa3b, v24
	v_mul_u32_u24_e32 v22, 0x48, v22
	v_exp_f32_e32 v24, v24
	v_or_b32_e32 v22, v22, v18
	v_lshl_add_u32 v22, v22, 1, s33
	v_sub_f32_e32 v25, v32, v40
	ds_write_b16_d16_hi v22, v23 offset:36864
	v_and_b32_e32 v23, 0xffff0000, v26
	v_mul_f32_e32 v25, 0x3fb8aa3b, v25
	v_mul_f32_e32 v23, v24, v23
	v_exp_f32_e32 v25, v25
	v_bfe_u32 v24, v23, 16, 1
	v_add3_u32 v23, v23, v24, s46
	ds_write_b16_d16_hi v19, v23 offset:38016
	v_lshlrev_b32_e32 v23, 16, v27
	v_mul_f32_e32 v23, v25, v23
	v_sub_f32_e32 v25, v33, v41
	v_mul_f32_e32 v25, 0x3fb8aa3b, v25
	v_exp_f32_e32 v25, v25
	v_bfe_u32 v24, v23, 16, 1
	v_add3_u32 v23, v23, v24, s46
	ds_write_b16_d16_hi v19, v23 offset:38160
	v_and_b32_e32 v23, 0xffff0000, v27
	v_mul_f32_e32 v23, v25, v23
	s_waitcnt lgkmcnt(4)
	v_sub_f32_e32 v25, v34, v42
	v_mul_f32_e32 v25, 0x3fb8aa3b, v25
	v_exp_f32_e32 v25, v25
	v_bfe_u32 v24, v23, 16, 1
	v_add3_u32 v23, v23, v24, s46
	ds_write_b16_d16_hi v19, v23 offset:38304
	v_lshlrev_b32_e32 v23, 16, v28
	v_mul_f32_e32 v23, v25, v23
	v_sub_f32_e32 v25, v35, v43
	v_mul_f32_e32 v25, 0x3fb8aa3b, v25
	v_exp_f32_e32 v25, v25
	v_bfe_u32 v24, v23, 16, 1
	v_add3_u32 v23, v23, v24, s46
	ds_write_b16_d16_hi v19, v23 offset:38448
	v_and_b32_e32 v23, 0xffff0000, v28
	v_mul_f32_e32 v23, v25, v23
	v_sub_f32_e32 v25, v36, v44
	v_mul_f32_e32 v25, 0x3fb8aa3b, v25
	v_exp_f32_e32 v25, v25
	v_bfe_u32 v24, v23, 16, 1
	v_add3_u32 v23, v23, v24, s46
	ds_write_b16_d16_hi v19, v23 offset:38592
	v_lshlrev_b32_e32 v23, 16, v29
	v_mul_f32_e32 v23, v25, v23
	v_sub_f32_e32 v25, v37, v45
	v_mul_f32_e32 v25, 0x3fb8aa3b, v25
	v_exp_f32_e32 v25, v25
	v_bfe_u32 v24, v23, 16, 1
	v_add3_u32 v23, v23, v24, s46
	ds_write_b16_d16_hi v19, v23 offset:38736
	v_and_b32_e32 v23, 0xffff0000, v29
	v_mul_f32_e32 v23, v25, v23
	ds_read_b128 v[24:27], v16 offset:32320
	ds_read_b128 v[28:31], v17 offset:64
	v_bfe_u32 v32, v23, 16, 1
	v_add3_u32 v23, v23, v32, s46
	ds_read_b128 v[32:35], v16 offset:32336
	ds_read_b128 v[36:39], v17 offset:80
	ds_write_b16_d16_hi v19, v23 offset:38880
	s_waitcnt lgkmcnt(3)
	v_sub_f32_e32 v24, v24, v28
	v_sub_f32_e32 v25, v25, v29
	v_mul_f32_e32 v24, 0x3fb8aa3b, v24
	v_mul_f32_e32 v25, 0x3fb8aa3b, v25
	v_exp_f32_e32 v24, v24
	v_exp_f32_e32 v25, v25
	v_or_b32_e32 v23, 16, v14
	s_waitcnt vmcnt(8)
	v_lshlrev_b32_e32 v28, 16, v4
	v_and_b32_e32 v4, 0xffff0000, v4
	v_mul_f32_e32 v24, v24, v28
	v_mul_u32_u24_e32 v23, 0x48, v23
	v_mul_f32_e32 v4, v25, v4
	v_sub_f32_e32 v25, v26, v30
	v_bfe_u32 v28, v24, 16, 1
	v_or_b32_e32 v23, v23, v18
	v_mul_f32_e32 v25, 0x3fb8aa3b, v25
	v_add3_u32 v24, v24, v28, s46
	v_lshl_add_u32 v23, v23, 1, s33
	v_exp_f32_e32 v25, v25
	ds_write_b16_d16_hi v23, v24 offset:36864
	v_bfe_u32 v24, v4, 16, 1
	v_add3_u32 v4, v4, v24, s46
	ds_write_b16_d16_hi v19, v4 offset:39168
	v_lshlrev_b32_e32 v4, 16, v5
	v_mul_f32_e32 v4, v25, v4
	v_sub_f32_e32 v25, v27, v31
	v_mul_f32_e32 v25, 0x3fb8aa3b, v25
	v_exp_f32_e32 v25, v25
	v_bfe_u32 v24, v4, 16, 1
	v_add3_u32 v4, v4, v24, s46
	s_waitcnt lgkmcnt(3)
	v_sub_f32_e32 v24, v32, v36
	ds_write_b16_d16_hi v19, v4 offset:39312
	v_and_b32_e32 v4, 0xffff0000, v5
	v_mul_f32_e32 v24, 0x3fb8aa3b, v24
	v_mul_f32_e32 v4, v25, v4
	v_exp_f32_e32 v24, v24
	v_bfe_u32 v5, v4, 16, 1
	v_add3_u32 v4, v4, v5, s46
	ds_write_b16_d16_hi v19, v4 offset:39456
	v_lshlrev_b32_e32 v4, 16, v6
	v_mul_f32_e32 v4, v24, v4
	v_sub_f32_e32 v24, v33, v37
	v_mul_f32_e32 v24, 0x3fb8aa3b, v24
	v_bfe_u32 v5, v4, 16, 1
	v_exp_f32_e32 v24, v24
	v_add3_u32 v4, v4, v5, s46
	ds_write_b16_d16_hi v19, v4 offset:39600
	v_and_b32_e32 v4, 0xffff0000, v6
	v_sub_f32_e32 v6, v34, v38
	v_mul_f32_e32 v6, 0x3fb8aa3b, v6
	v_mul_f32_e32 v4, v24, v4
	v_exp_f32_e32 v6, v6
	v_bfe_u32 v5, v4, 16, 1
	v_add3_u32 v4, v4, v5, s46
	ds_write_b16_d16_hi v19, v4 offset:39744
	v_lshlrev_b32_e32 v4, 16, v7
	v_mul_f32_e32 v4, v6, v4
	v_sub_f32_e32 v6, v35, v39
	v_mul_f32_e32 v6, 0x3fb8aa3b, v6
	v_exp_f32_e32 v6, v6
	v_bfe_u32 v5, v4, 16, 1
	v_add3_u32 v4, v4, v5, s46
	ds_write_b16_d16_hi v19, v4 offset:39888
	v_and_b32_e32 v4, 0xffff0000, v7
	v_mul_f32_e32 v28, v6, v4
	ds_read_b128 v[4:7], v16 offset:32352
	ds_read_b128 v[24:27], v17 offset:96
	v_bfe_u32 v29, v28, 16, 1
	v_add3_u32 v36, v28, v29, s46
	ds_read_b128 v[28:31], v16 offset:32368
	ds_read_b128 v[32:35], v17 offset:112
	v_or_b32_e32 v17, 24, v14
	s_waitcnt lgkmcnt(2)
	v_sub_f32_e32 v4, v4, v24
	v_sub_f32_e32 v5, v5, v25
	v_mul_f32_e32 v4, 0x3fb8aa3b, v4
	v_mul_f32_e32 v5, 0x3fb8aa3b, v5
	v_exp_f32_e32 v4, v4
	v_exp_f32_e32 v5, v5
	v_lshlrev_b32_e32 v24, 16, v0
	v_and_b32_e32 v0, 0xffff0000, v0
	v_mul_f32_e32 v4, v4, v24
	v_mul_u32_u24_e32 v17, 0x48, v17
	v_mul_f32_e32 v0, v5, v0
	v_sub_f32_e32 v5, v6, v26
	v_bfe_u32 v24, v4, 16, 1
	v_or_b32_e32 v17, v17, v18
	v_mul_f32_e32 v5, 0x3fb8aa3b, v5
	v_add3_u32 v4, v4, v24, s46
	v_lshl_add_u32 v124, v17, 1, s33
	v_exp_f32_e32 v5, v5
	ds_write_b16_d16_hi v19, v36 offset:40032
	ds_write_b16_d16_hi v124, v4 offset:36864
	v_bfe_u32 v4, v0, 16, 1
	v_add3_u32 v0, v0, v4, s46
	ds_write_b16_d16_hi v19, v0 offset:40320
	v_lshlrev_b32_e32 v0, 16, v1
	v_mul_f32_e32 v0, v5, v0
	v_sub_f32_e32 v5, v7, v27
	v_mul_f32_e32 v5, 0x3fb8aa3b, v5
	v_exp_f32_e32 v5, v5
	v_bfe_u32 v4, v0, 16, 1
	v_add3_u32 v0, v0, v4, s46
	s_waitcnt lgkmcnt(3)
	v_sub_f32_e32 v4, v28, v32
	ds_write_b16_d16_hi v19, v0 offset:40464
	v_and_b32_e32 v0, 0xffff0000, v1
	v_mul_f32_e32 v4, 0x3fb8aa3b, v4
	v_mul_f32_e32 v0, v5, v0
	v_exp_f32_e32 v4, v4
	v_bfe_u32 v1, v0, 16, 1
	v_add3_u32 v0, v0, v1, s46
	ds_write_b16_d16_hi v19, v0 offset:40608
	v_lshlrev_b32_e32 v0, 16, v2
	v_mul_f32_e32 v0, v4, v0
	v_sub_f32_e32 v4, v29, v33
	v_mul_f32_e32 v4, 0x3fb8aa3b, v4
	v_bfe_u32 v1, v0, 16, 1
	v_exp_f32_e32 v4, v4
	v_add3_u32 v0, v0, v1, s46
	ds_write_b16_d16_hi v19, v0 offset:40752
	v_and_b32_e32 v0, 0xffff0000, v2
	v_sub_f32_e32 v2, v30, v34
	v_mul_f32_e32 v2, 0x3fb8aa3b, v2
	v_mul_f32_e32 v0, v4, v0
	v_exp_f32_e32 v2, v2
	v_bfe_u32 v1, v0, 16, 1
	v_add3_u32 v0, v0, v1, s46
	ds_write_b16_d16_hi v19, v0 offset:40896
	v_lshlrev_b32_e32 v0, 16, v3
	v_mul_f32_e32 v0, v2, v0
	v_sub_f32_e32 v2, v31, v35
	v_mul_f32_e32 v2, 0x3fb8aa3b, v2
	v_exp_f32_e32 v2, v2
	v_bfe_u32 v1, v0, 16, 1
	v_add3_u32 v0, v0, v1, s46
	ds_write_b16_d16_hi v19, v0 offset:41040
	v_and_b32_e32 v0, 0xffff0000, v3
	v_mul_f32_e32 v0, v2, v0
	v_bfe_u32 v1, v0, 16, 1
	v_add3_u32 v0, v0, v1, s46
	ds_write_b16_d16_hi v19, v0 offset:41184
	v_lshl_add_u64 v[0:1], v[10:11], 0, s[18:19]
	v_lshl_add_u64 v[0:1], v[0:1], 0, v[8:9]
	s_waitcnt lgkmcnt(0)
	s_barrier
; __device__ __forceinline__ f32x4 mfma16(bf16x8 a, bf16x8 b, f32x4 c) { return __builtin_amdgcn_mfma_f32_16x16x32_bf16(a, b, c, 0, 0, 0); }
; __device__ void phaseG1_task(const Params& p, int task, char* lds) {
;     ...
;         __syncthreads();
;         {
;             const int s = lane, ec = wave * 32;
;             const bf16_t* vp = Z + (size_t)(tok0 + s) * ZC + ZV_G + h * 256 + eh * 128 + ec;
; #pragma unroll
;             for (int v4 = 0; v4 < 4; v4++) {
;                 const u32x4 vv = *(const u32x4*)(vp + v4 * 8);
;                 const unsigned vw[4] = {vv.x, vv.y, vv.z, vv.w};
; #pragma unroll
;                 for (int j = 0; j < 8; j++) vT[(ec + v4 * 8 + j) * 72 + s] = (bf16_t)((j & 1) ? (vw[j >> 1] >> 16) : (vw[j >> 1] & 0xffffu));
;             }
;         }
;         __syncthreads();
;         f32x4 acc[8][2];
; #pragma unroll
;         for (int dt = 0; dt < 8; dt++) { acc[dt][0] = (f32x4){0.f, 0.f, 0.f, 0.f}; acc[dt][1] = (f32x4){0.f, 0.f, 0.f, 0.f}; }
; #pragma unroll
;         for (int ks = 0; ks < 2; ks++) {
;             bf16x8 bv[2];
; #pragma unroll
;             for (int x = 0; x < 2; x++) bv[x] = ld_frag(vT + ((2 * wave + x) * 16 + r) * 72 + ks * 32 + q * 8);
; #pragma unroll
;             for (int dt = 0; dt < 8; dt++) {
;                 const bf16x8 a = ld_frag(klT + (dt * 16 + r) * 72 + ks * 32 + q * 8);
; #pragma unroll
;                 for (int x = 0; x < 2; x++) acc[dt][x] = mfma16(a, bv[x], acc[dt][x]);
;             }
;         }
; #pragma unroll
;         for (int dt = 0; dt < 8; dt++)
; #pragma unroll
;             for (int x = 0; x < 2; x++) {
;                 const int e = eh * 128 + (2 * wave + x) * 16 + r, d = dt * 16 + 4 * q;
;                 const f32x4 v = acc[dt][x];
;                 *(u32x2*)(L + ((size_t)task * 256 + e) * 128 + d) = (u32x2){pack2(v[0], v[1]), pack2(v[2], v[3])};
;             }
	s_waitcnt vmcnt(4)
	v_mov_b32_e32 v2, v132
	v_mov_b32_e32 v3, v133
	v_mov_b32_e32 v4, v134
	v_mov_b32_e32 v5, v135
	v_mov_b32_e32 v24, v136
	v_mov_b32_e32 v25, v137
	v_mov_b32_e32 v26, v138
	v_mov_b32_e32 v27, v139
	v_mov_b32_e32 v28, v140
	v_mov_b32_e32 v29, v141
	v_mov_b32_e32 v30, v142
	v_mov_b32_e32 v31, v143
	v_mov_b32_e32 v32, v144
	v_mov_b32_e32 v33, v145
	v_mov_b32_e32 v34, v146
	v_mov_b32_e32 v35, v147
	v_mul_u32_u24_e32 v8, 0x8c, v14
	v_and_b32_e32 v6, 15, v12
	v_and_b32_e32 v7, 48, v12
	v_add3_u32 v125, v16, v8, v15
	v_add_u32_e32 v7, s33, v7
	v_or_b32_e32 v12, v14, v6
	v_and_b32_e32 v8, 24, v13
	ds_write_b16 v21, v2 offset:55296
	ds_write_b16_d16_hi v125, v2 offset:55440
	ds_write_b16 v125, v3 offset:55584
	ds_write_b16_d16_hi v125, v3 offset:55728
	ds_write_b16 v125, v4 offset:55872
	ds_write_b16_d16_hi v125, v4 offset:56016
	ds_write_b16 v125, v5 offset:56160
	ds_write_b16_d16_hi v125, v5 offset:56304
	ds_write_b16 v22, v24 offset:55296
	ds_write_b16_d16_hi v125, v24 offset:56592
	ds_write_b16 v125, v25 offset:56736
	ds_write_b16_d16_hi v125, v25 offset:56880
	ds_write_b16 v125, v26 offset:57024
	ds_write_b16_d16_hi v125, v26 offset:57168
	ds_write_b16 v125, v27 offset:57312
	ds_write_b16_d16_hi v125, v27 offset:57456
	ds_write_b16 v23, v28 offset:55296
	ds_write_b16_d16_hi v125, v28 offset:57744
	ds_write_b16 v125, v29 offset:57888
	ds_write_b16_d16_hi v125, v29 offset:58032
	ds_write_b16 v125, v30 offset:58176
	ds_write_b16_d16_hi v125, v30 offset:58320
	ds_write_b16 v125, v31 offset:58464
	ds_write_b16_d16_hi v125, v31 offset:58608
	ds_write_b16 v124, v32 offset:55296
	ds_write_b16_d16_hi v125, v32 offset:58896
	ds_write_b16 v125, v33 offset:59040
	ds_write_b16_d16_hi v125, v33 offset:59184
	ds_write_b16 v125, v34 offset:59328
	ds_write_b16_d16_hi v125, v34 offset:59472
	ds_write_b16 v125, v35 offset:59616
	ds_write_b16_d16_hi v125, v35 offset:59760
	v_mul_u32_u24_e32 v2, 0x48, v6
	v_lshl_add_u32 v126, v2, 1, v7
	s_waitcnt lgkmcnt(0)
	s_barrier
	ds_read_b128 v[2:5], v126 offset:36864
	v_mul_u32_u24_e32 v6, 0x48, v12
	v_lshl_add_u32 v127, v6, 1, v7
	ds_read_b128 v[14:17], v127 offset:55296
	ds_read_b128 v[24:27], v127 offset:55360
	ds_read_b128 v[28:31], v126 offset:36928
	ds_read_b128 v[36:39], v127 offset:57600
	ds_read_b128 v[40:43], v127 offset:57664
	ds_read_b128 v[44:47], v126 offset:39168
	ds_read_b128 v[48:51], v126 offset:39232
	s_waitcnt lgkmcnt(6)
	v_mfma_f32_16x16x32_bf16 v[32:35], v[2:5], v[14:17], 0
	ds_read_b128 v[56:59], v126 offset:41472
	ds_read_b128 v[60:63], v126 offset:41536
	ds_read_b128 v[68:71], v126 offset:43776
	ds_read_b128 v[72:75], v126 offset:43840
	ds_read_b128 v[80:83], v126 offset:46080
	ds_read_b128 v[84:87], v126 offset:46144
	s_waitcnt lgkmcnt(9)
	v_mfma_f32_16x16x32_bf16 v[2:5], v[2:5], v[36:39], 0
	ds_read_b128 v[92:95], v126 offset:48384
	ds_read_b128 v[96:99], v126 offset:48448
	ds_read_b128 v[104:107], v126 offset:50688
	ds_read_b128 v[108:111], v126 offset:50752
	ds_read_b128 v[116:119], v126 offset:52992
	ds_read_b128 v[120:123], v126 offset:53056
	s_waitcnt lgkmcnt(13)
	v_mfma_f32_16x16x32_bf16 v[52:55], v[44:47], v[14:17], 0
	v_mfma_f32_16x16x32_bf16 v[44:47], v[44:47], v[36:39], 0
	s_waitcnt lgkmcnt(11)
	v_mfma_f32_16x16x32_bf16 v[64:67], v[56:59], v[14:17], 0
	v_mfma_f32_16x16x32_bf16 v[32:35], v[28:31], v[24:27], v[32:35]
	v_mfma_f32_16x16x32_bf16 v[56:59], v[56:59], v[36:39], 0
	v_mfma_f32_16x16x32_bf16 v[4:7], v[28:31], v[40:43], v[2:5]
	s_nop 5
	v_cvt_pk_bf16_f32 v11, v34, v35
	v_mov_b32_e32 v35, v9
	v_cvt_pk_bf16_f32 v10, v32, v33
	s_waitcnt lgkmcnt(9)
	v_mfma_f32_16x16x32_bf16 v[76:79], v[68:71], v[14:17], 0
	v_lshl_add_u64 v[2:3], s[4:5], 0, v[8:9]
	v_lshlrev_b32_e32 v8, 8, v12
	v_or_b32_e32 v34, 0x1000, v8
	v_mfma_f32_16x16x32_bf16 v[28:31], v[48:51], v[24:27], v[52:55]
	v_cvt_pk_bf16_f32 v4, v4, v5
	v_cvt_pk_bf16_f32 v5, v6, v7
	v_lshl_add_u64 v[6:7], v[2:3], 0, v[34:35]
	v_mfma_f32_16x16x32_bf16 v[68:71], v[68:71], v[36:39], 0
	v_lshl_add_u64 v[32:33], v[2:3], 0, v[8:9]
	global_store_dwordx2 v[6:7], v[4:5], off
	v_lshl_add_u64 v[4:5], v[2:3], 0, 32
	v_mfma_f32_16x16x32_bf16 v[44:47], v[48:51], v[40:43], v[44:47]
	v_cvt_pk_bf16_f32 v6, v28, v29
	v_cvt_pk_bf16_f32 v7, v30, v31
	global_store_dwordx2 v[32:33], v[10:11], off
	s_waitcnt lgkmcnt(7)
	v_mfma_f32_16x16x32_bf16 v[88:91], v[80:83], v[14:17], 0
	global_store_dwordx2 v[32:33], v[6:7], off offset:32
	s_nop 1
	v_cvt_pk_bf16_f32 v6, v44, v45
	v_cvt_pk_bf16_f32 v7, v46, v47
	v_mfma_f32_16x16x32_bf16 v[48:51], v[60:63], v[24:27], v[64:67]
	v_lshl_add_u64 v[10:11], v[4:5], 0, v[34:35]
	global_store_dwordx2 v[10:11], v[6:7], off
	v_lshl_add_u64 v[6:7], v[2:3], 0, 64
	v_mfma_f32_16x16x32_bf16 v[80:83], v[80:83], v[36:39], 0
	v_lshl_add_u64 v[12:13], v[6:7], 0, v[34:35]
	s_nop 2
	v_cvt_pk_bf16_f32 v10, v48, v49
	v_cvt_pk_bf16_f32 v11, v50, v51
	v_mfma_f32_16x16x32_bf16 v[52:55], v[60:63], v[40:43], v[56:59]
	global_store_dwordx2 v[32:33], v[10:11], off offset:64
	s_waitcnt lgkmcnt(5)
	v_mfma_f32_16x16x32_bf16 v[100:103], v[92:95], v[14:17], 0
	v_mfma_f32_16x16x32_bf16 v[56:59], v[72:75], v[24:27], v[76:79]
	s_nop 3
	v_cvt_pk_bf16_f32 v10, v52, v53
	v_cvt_pk_bf16_f32 v11, v54, v55
	global_store_dwordx2 v[12:13], v[10:11], off
	v_mfma_f32_16x16x32_bf16 v[92:95], v[92:95], v[36:39], 0
	v_lshl_add_u64 v[10:11], v[2:3], 0, s[22:23]
	v_cvt_pk_bf16_f32 v12, v56, v57
	v_cvt_pk_bf16_f32 v13, v58, v59
	s_waitcnt lgkmcnt(3)
	v_mfma_f32_16x16x32_bf16 v[112:115], v[104:107], v[14:17], 0
	global_store_dwordx2 v[32:33], v[12:13], off offset:96
	s_waitcnt lgkmcnt(1)
; __device__ void phaseG1_task(const Params& p, int task, char* lds) {
;     ...
;         {
;             const int s = lane, ec = wave * 32;
;             const bf16_t* vp = Z + (size_t)(tok0 + s) * ZC + ZV_G + h * 256 + eh * 128 + ec;
; #pragma unroll
;             for (int v4 = 0; v4 < 4; v4++) {
;                 const u32x4 vv = *(const u32x4*)(vp + v4 * 8);
;                 const unsigned vw[4] = {vv.x, vv.y, vv.z, vv.w};
; #pragma unroll
;                 for (int j = 0; j < 8; j++) vT[(ec + v4 * 8 + j) * 72 + s] = (bf16_t)((j & 1) ? (vw[j >> 1] >> 16) : (vw[j >> 1] & 0xffffu));
;             }
;         }
;     ...
; #pragma unroll
;         for (int dt = 0; dt < 8; dt++)
; #pragma unroll
;             for (int x = 0; x < 2; x++) {
;                 const int e = eh * 128 + (2 * wave + x) * 16 + r, d = dt * 16 + 4 * q;
;                 const f32x4 v = acc[dt][x];
;                 *(u32x2*)(L + ((size_t)task * 256 + e) * 128 + d) = (u32x2){pack2(v[0], v[1]), pack2(v[2], v[3])};
;             }
	v_mfma_f32_16x16x32_bf16 v[14:17], v[116:119], v[14:17], 0
	v_mfma_f32_16x16x32_bf16 v[60:63], v[72:75], v[40:43], v[68:71]
	v_mfma_f32_16x16x32_bf16 v[64:67], v[84:87], v[24:27], v[88:91]
	v_mfma_f32_16x16x32_bf16 v[104:107], v[104:107], v[36:39], 0
	s_nop 5
	v_cvt_pk_bf16_f32 v12, v60, v61
	v_cvt_pk_bf16_f32 v13, v62, v63
	v_mfma_f32_16x16x32_bf16 v[68:71], v[84:87], v[40:43], v[80:83]
	v_mfma_f32_16x16x32_bf16 v[72:75], v[96:99], v[24:27], v[100:103]
	v_mfma_f32_16x16x32_bf16 v[36:39], v[116:119], v[36:39], 0
	v_mfma_f32_16x16x32_bf16 v[76:79], v[96:99], v[40:43], v[92:95]
	v_mfma_f32_16x16x32_bf16 v[80:83], v[108:111], v[24:27], v[112:115]
	s_waitcnt lgkmcnt(0)
	v_mfma_f32_16x16x32_bf16 v[24:27], v[120:123], v[24:27], v[14:17]
	s_nop 2
	v_lshl_add_u64 v[14:15], v[10:11], 0, v[34:35]
	global_store_dwordx2 v[14:15], v[12:13], off
	v_lshl_add_u64 v[12:13], v[2:3], 0, s[24:25]
	v_cvt_pk_bf16_f32 v14, v64, v65
	v_cvt_pk_bf16_f32 v15, v66, v67
	v_mfma_f32_16x16x32_bf16 v[84:87], v[108:111], v[40:43], v[104:107]
	global_store_dwordx2 v[32:33], v[14:15], off offset:128
	v_cvt_pk_bf16_f32 v14, v68, v69
	v_cvt_pk_bf16_f32 v15, v70, v71
	v_lshl_add_u64 v[16:17], v[12:13], 0, v[34:35]
	global_store_dwordx2 v[16:17], v[14:15], off
	v_lshl_add_u64 v[14:15], v[2:3], 0, s[26:27]
	v_cvt_pk_bf16_f32 v16, v72, v73
	v_cvt_pk_bf16_f32 v17, v74, v75
	v_mfma_f32_16x16x32_bf16 v[36:39], v[120:123], v[40:43], v[36:39]
	global_store_dwordx2 v[32:33], v[16:17], off offset:160
	v_cvt_pk_bf16_f32 v16, v76, v77
	v_cvt_pk_bf16_f32 v17, v78, v79
	v_lshl_add_u64 v[18:19], v[14:15], 0, v[34:35]
	global_store_dwordx2 v[18:19], v[16:17], off
	v_lshl_add_u64 v[16:17], v[2:3], 0, s[28:29]
	v_cvt_pk_bf16_f32 v18, v80, v81
	v_cvt_pk_bf16_f32 v19, v82, v83
	global_store_dwordx2 v[32:33], v[18:19], off offset:192
	v_cvt_pk_bf16_f32 v18, v84, v85
	v_cvt_pk_bf16_f32 v19, v86, v87
	v_lshl_add_u64 v[28:29], v[16:17], 0, v[34:35]
	global_store_dwordx2 v[28:29], v[18:19], off
	v_lshl_add_u64 v[18:19], v[2:3], 0, s[30:31]
	v_cvt_pk_bf16_f32 v24, v24, v25
	v_cvt_pk_bf16_f32 v25, v26, v27
	global_store_dwordx2 v[32:33], v[24:25], off offset:224
	v_cvt_pk_bf16_f32 v24, v36, v37
	v_cvt_pk_bf16_f32 v25, v38, v39
	v_lshl_add_u64 v[26:27], v[18:19], 0, v[34:35]
	global_store_dwordx2 v[26:27], v[24:25], off
	s_barrier
	s_waitcnt vmcnt(16)
	v_mov_b32_e32 v24, v148
	v_mov_b32_e32 v25, v149
	v_mov_b32_e32 v26, v150
	v_mov_b32_e32 v27, v151
	v_mov_b32_e32 v28, v152
	v_mov_b32_e32 v29, v153
	v_mov_b32_e32 v30, v154
	v_mov_b32_e32 v31, v155
	v_mov_b32_e32 v32, v160
	v_mov_b32_e32 v33, v161
	v_mov_b32_e32 v34, v162
	v_mov_b32_e32 v35, v163
	v_mov_b32_e32 v36, v164
	v_mov_b32_e32 v37, v165
	v_mov_b32_e32 v38, v166
	v_mov_b32_e32 v39, v167
	ds_write_b16 v21, v24 offset:55296
	ds_write_b16_d16_hi v125, v24 offset:55440
	ds_write_b16 v125, v25 offset:55584
	ds_write_b16_d16_hi v125, v25 offset:55728
	ds_write_b16 v125, v26 offset:55872
	ds_write_b16_d16_hi v125, v26 offset:56016
	ds_write_b16 v125, v27 offset:56160
	ds_write_b16_d16_hi v125, v27 offset:56304
	ds_write_b16 v22, v28 offset:55296
	ds_write_b16_d16_hi v125, v28 offset:56592
	ds_write_b16 v125, v29 offset:56736
	ds_write_b16_d16_hi v125, v29 offset:56880
	ds_write_b16 v125, v30 offset:57024
	ds_write_b16_d16_hi v125, v30 offset:57168
	ds_write_b16 v125, v31 offset:57312
	ds_write_b16_d16_hi v125, v31 offset:57456
	ds_write_b16 v23, v32 offset:55296
	ds_write_b16_d16_hi v125, v32 offset:57744
	ds_write_b16 v125, v33 offset:57888
	ds_write_b16_d16_hi v125, v33 offset:58032
	ds_write_b16 v125, v34 offset:58176
	ds_write_b16_d16_hi v125, v34 offset:58320
	ds_write_b16 v125, v35 offset:58464
	ds_write_b16_d16_hi v125, v35 offset:58608
	ds_write_b16 v124, v36 offset:55296
	ds_write_b16_d16_hi v125, v36 offset:58896
	ds_write_b16 v125, v37 offset:59040
	ds_write_b16_d16_hi v125, v37 offset:59184
	ds_write_b16 v125, v38 offset:59328
	ds_write_b16_d16_hi v125, v38 offset:59472
	ds_write_b16 v125, v39 offset:59616
	ds_write_b16_d16_hi v125, v39 offset:59760
	s_waitcnt lgkmcnt(0)
	s_barrier
; __device__ __forceinline__ f32x4 mfma16(bf16x8 a, bf16x8 b, f32x4 c) { return __builtin_amdgcn_mfma_f32_16x16x32_bf16(a, b, c, 0, 0, 0); }
; __device__ void phaseG1_task(const Params& p, int task, char* lds) {
;     ...
; #pragma unroll
;         for (int ks = 0; ks < 2; ks++) {
;             bf16x8 bv[2];
; #pragma unroll
;             for (int x = 0; x < 2; x++) bv[x] = ld_frag(vT + ((2 * wave + x) * 16 + r) * 72 + ks * 32 + q * 8);
; #pragma unroll
;             for (int dt = 0; dt < 8; dt++) {
;                 const bf16x8 a = ld_frag(klT + (dt * 16 + r) * 72 + ks * 32 + q * 8);
; #pragma unroll
;                 for (int x = 0; x < 2; x++) acc[dt][x] = mfma16(a, bv[x], acc[dt][x]);
;             }
;         }
; #pragma unroll
;         for (int dt = 0; dt < 8; dt++)
; #pragma unroll
;             for (int x = 0; x < 2; x++) {
;                 const int e = eh * 128 + (2 * wave + x) * 16 + r, d = dt * 16 + 4 * q;
;                 const f32x4 v = acc[dt][x];
;                 *(u32x2*)(L + ((size_t)task * 256 + e) * 128 + d) = (u32x2){pack2(v[0], v[1]), pack2(v[2], v[3])};
;             }
;     }
	ds_read_b128 v[22:25], v126 offset:36864
	ds_read_b128 v[26:29], v127 offset:55296
	ds_read_b128 v[30:33], v127 offset:55360
	ds_read_b128 v[34:37], v126 offset:36928
	ds_read_b128 v[42:45], v127 offset:57600
	ds_read_b128 v[46:49], v127 offset:57664
	ds_read_b128 v[50:53], v126 offset:39168
	ds_read_b128 v[54:57], v126 offset:39232
	s_waitcnt lgkmcnt(6)
	v_mfma_f32_16x16x32_bf16 v[38:41], v[22:25], v[26:29], 0
	ds_read_b128 v[62:65], v126 offset:41472
	ds_read_b128 v[66:69], v126 offset:41536
	ds_read_b128 v[74:77], v126 offset:43776
	ds_read_b128 v[78:81], v126 offset:43840
	ds_read_b128 v[86:89], v126 offset:46080
	ds_read_b128 v[90:93], v126 offset:46144
	s_waitcnt lgkmcnt(9)
	v_mfma_f32_16x16x32_bf16 v[22:25], v[22:25], v[42:45], 0
	ds_read_b128 v[98:101], v126 offset:48384
	ds_read_b128 v[102:105], v126 offset:48448
	ds_read_b128 v[110:113], v126 offset:50688
	ds_read_b128 v[114:117], v126 offset:50752
	ds_read_b128 v[122:125], v126 offset:52992
	ds_read_b128 v[126:129], v126 offset:53056
	s_waitcnt lgkmcnt(13)
	v_mfma_f32_16x16x32_bf16 v[58:61], v[50:53], v[26:29], 0
	v_mfma_f32_16x16x32_bf16 v[50:53], v[50:53], v[42:45], 0
	v_mfma_f32_16x16x32_bf16 v[38:41], v[34:37], v[30:33], v[38:41]
	s_waitcnt lgkmcnt(11)
	v_mfma_f32_16x16x32_bf16 v[70:73], v[62:65], v[26:29], 0
	v_mfma_f32_16x16x32_bf16 v[62:65], v[62:65], v[42:45], 0
	s_nop 4
	v_cvt_pk_bf16_f32 v0, v38, v39
	v_or_b32_e32 v38, 0x8000, v8
	v_mov_b32_e32 v39, v9
	v_mfma_f32_16x16x32_bf16 v[22:25], v[34:37], v[46:49], v[22:25]
	v_cvt_pk_bf16_f32 v1, v40, v41
	v_lshl_add_u64 v[40:41], v[2:3], 0, v[38:39]
	v_or_b32_e32 v8, 0x9000, v8
	s_waitcnt lgkmcnt(9)
	v_mfma_f32_16x16x32_bf16 v[82:85], v[74:77], v[26:29], 0
	global_store_dwordx2 v[40:41], v[0:1], off
	s_nop 1
	v_cvt_pk_bf16_f32 v0, v22, v23
	v_cvt_pk_bf16_f32 v1, v24, v25
	v_mfma_f32_16x16x32_bf16 v[34:37], v[54:57], v[30:33], v[58:61]
	v_lshl_add_u64 v[2:3], v[2:3], 0, v[8:9]
	global_store_dwordx2 v[2:3], v[0:1], off
	v_lshl_add_u64 v[2:3], v[4:5], 0, v[38:39]
	v_mfma_f32_16x16x32_bf16 v[74:77], v[74:77], v[42:45], 0
	v_mfma_f32_16x16x32_bf16 v[50:53], v[54:57], v[46:49], v[50:53]
	s_nop 2
	v_cvt_pk_bf16_f32 v0, v34, v35
	v_cvt_pk_bf16_f32 v1, v36, v37
	global_store_dwordx2 v[2:3], v[0:1], off
	s_waitcnt lgkmcnt(7)
	v_mfma_f32_16x16x32_bf16 v[94:97], v[86:89], v[26:29], 0
	v_lshl_add_u64 v[2:3], v[4:5], 0, v[8:9]
	v_cvt_pk_bf16_f32 v0, v50, v51
	v_cvt_pk_bf16_f32 v1, v52, v53
	v_mfma_f32_16x16x32_bf16 v[54:57], v[66:69], v[30:33], v[70:73]
	global_store_dwordx2 v[2:3], v[0:1], off
	v_lshl_add_u64 v[2:3], v[6:7], 0, v[38:39]
	v_mfma_f32_16x16x32_bf16 v[86:89], v[86:89], v[42:45], 0
	v_mfma_f32_16x16x32_bf16 v[58:61], v[66:69], v[46:49], v[62:65]
	s_nop 3
	v_cvt_pk_bf16_f32 v0, v54, v55
	v_cvt_pk_bf16_f32 v1, v56, v57
	global_store_dwordx2 v[2:3], v[0:1], off
	s_waitcnt lgkmcnt(5)
	v_mfma_f32_16x16x32_bf16 v[106:109], v[98:101], v[26:29], 0
	v_lshl_add_u64 v[2:3], v[6:7], 0, v[8:9]
	v_cvt_pk_bf16_f32 v0, v58, v59
	v_cvt_pk_bf16_f32 v1, v60, v61
	v_mfma_f32_16x16x32_bf16 v[62:65], v[78:81], v[30:33], v[82:85]
	global_store_dwordx2 v[2:3], v[0:1], off
	v_lshl_add_u64 v[2:3], v[10:11], 0, v[38:39]
	v_mfma_f32_16x16x32_bf16 v[98:101], v[98:101], v[42:45], 0
	v_mfma_f32_16x16x32_bf16 v[66:69], v[78:81], v[46:49], v[74:77]
	s_nop 3
	v_cvt_pk_bf16_f32 v0, v62, v63
	v_cvt_pk_bf16_f32 v1, v64, v65
	global_store_dwordx2 v[2:3], v[0:1], off
	s_waitcnt lgkmcnt(3)
	v_mfma_f32_16x16x32_bf16 v[118:121], v[110:113], v[26:29], 0
	v_lshl_add_u64 v[2:3], v[10:11], 0, v[8:9]
	v_cvt_pk_bf16_f32 v0, v66, v67
	v_cvt_pk_bf16_f32 v1, v68, v69
	v_mfma_f32_16x16x32_bf16 v[70:73], v[90:93], v[30:33], v[94:97]
	global_store_dwordx2 v[2:3], v[0:1], off
	v_lshl_add_u64 v[2:3], v[12:13], 0, v[38:39]
	v_mfma_f32_16x16x32_bf16 v[110:113], v[110:113], v[42:45], 0
	v_mfma_f32_16x16x32_bf16 v[74:77], v[90:93], v[46:49], v[86:89]
	s_nop 3
	v_cvt_pk_bf16_f32 v0, v70, v71
	v_cvt_pk_bf16_f32 v1, v72, v73
	global_store_dwordx2 v[2:3], v[0:1], off
	s_waitcnt lgkmcnt(1)
	v_mfma_f32_16x16x32_bf16 v[26:29], v[122:125], v[26:29], 0
	v_lshl_add_u64 v[2:3], v[12:13], 0, v[8:9]
	v_cvt_pk_bf16_f32 v0, v74, v75
	v_cvt_pk_bf16_f32 v1, v76, v77
	v_mfma_f32_16x16x32_bf16 v[78:81], v[102:105], v[30:33], v[106:109]
	global_store_dwordx2 v[2:3], v[0:1], off
	v_lshl_add_u64 v[2:3], v[14:15], 0, v[38:39]
	v_mfma_f32_16x16x32_bf16 v[42:45], v[122:125], v[42:45], 0
	v_mfma_f32_16x16x32_bf16 v[82:85], v[102:105], v[46:49], v[98:101]
	s_nop 3
	v_cvt_pk_bf16_f32 v0, v78, v79
	v_cvt_pk_bf16_f32 v1, v80, v81
	global_store_dwordx2 v[2:3], v[0:1], off
	v_mfma_f32_16x16x32_bf16 v[86:89], v[114:117], v[30:33], v[118:121]
	v_lshl_add_u64 v[2:3], v[14:15], 0, v[8:9]
	v_cvt_pk_bf16_f32 v0, v82, v83
	v_cvt_pk_bf16_f32 v1, v84, v85
	v_mfma_f32_16x16x32_bf16 v[90:93], v[114:117], v[46:49], v[110:113]
	global_store_dwordx2 v[2:3], v[0:1], off
	s_nop 2
	v_cvt_pk_bf16_f32 v0, v86, v87
	v_cvt_pk_bf16_f32 v1, v88, v89
	s_waitcnt lgkmcnt(0)
	v_mfma_f32_16x16x32_bf16 v[26:29], v[126:129], v[30:33], v[26:29]
	v_lshl_add_u64 v[2:3], v[16:17], 0, v[38:39]
	global_store_dwordx2 v[2:3], v[0:1], off
	v_cvt_pk_bf16_f32 v0, v90, v91
	v_mfma_f32_16x16x32_bf16 v[30:33], v[126:129], v[46:49], v[42:45]
	v_cvt_pk_bf16_f32 v1, v92, v93
	v_lshl_add_u64 v[2:3], v[16:17], 0, v[8:9]
	global_store_dwordx2 v[2:3], v[0:1], off
	s_nop 0
	v_cvt_pk_bf16_f32 v0, v26, v27
	v_cvt_pk_bf16_f32 v1, v28, v29
	v_lshl_add_u64 v[2:3], v[18:19], 0, v[38:39]
	global_store_dwordx2 v[2:3], v[0:1], off
	v_cvt_pk_bf16_f32 v0, v30, v31
	v_cvt_pk_bf16_f32 v1, v32, v33
	v_lshl_add_u64 v[2:3], v[18:19], 0, v[8:9]
	global_store_dwordx2 v[2:3], v[0:1], off
	s_barrier
	s_cbranch_scc1 .LBB0_387
